# gdn scan: counted wait split in two (Bc before the in-place store, M fragments only before the MFMAs)
# speedup vs baseline: 1.0048x; 1.0048x over previous
; __device__ __forceinline__ float bf_lo(unsigned u) { return __uint_as_float(u << 16); }
; __device__ __forceinline__ float bf_hi(unsigned u) { return __uint_as_float(u & 0xffff0000u); }
; __device__ __forceinline__ unsigned pk2(float lo, float hi) { return pg8::cvt_pk_bf16(lo, hi); }
; __device__ __forceinline__ void scan_phase(const Ctx& X, int wave, int lane) {
;     ...
;         SCAN_LOAD_G(0, 0) SCAN_LOAD_G(1, 1) SCAN_LOAD_G(2, 2)
; #pragma unroll 1
;         for (int c0 = 0; c0 < NCH; c0 += 4) {
; #pragma unroll
;             for (int k = 0; k < 4; ++k) {
;                 const int c = c0 + k;
;                 SCAN_LOAD_G((k + 3) & 3, c + 3)
;                 bf16_t* bcc = bc0 + (size_t)c * 4096;
;                 u32x2 sp[4];
; #pragma unroll
;                 for (int t = 0; t < 4; ++t) { sp[t].x = pk2(S[t][0], S[t][1]); sp[t].y = pk2(S[t][2], S[t][3]);
;                     asm volatile("" : "+v"(sp[t].x) : "v"(cb[k][t].x));
;                     *(u32x2*)(bcc + 256 * t) = sp[t]; }
;                 bf16x8 bfr[2];
; #pragma unroll
;                 for (int s2 = 0; s2 < 2; ++s2) { u32x4 w; w.x = sp[2 * s2].x; w.y = sp[2 * s2].y; w.z = sp[2 * s2 + 1].x; w.w = sp[2 * s2 + 1].y; bfr[s2] = __builtin_bit_cast(bf16x8, w); }
; #pragma unroll
;                 for (int t = 0; t < 4; ++t) {
;                     f32x4 acc = (f32x4){bf_lo(cb[k][t].x), bf_hi(cb[k][t].x), bf_lo(cb[k][t].y), bf_hi(cb[k][t].y)};
; #pragma unroll
;                     for (int s2 = 0; s2 < 2; ++s2) { u32x4 w; w.x = ca[k][t][s2][0].x; w.y = ca[k][t][s2][0].y; w.z = ca[k][t][s2][1].x; w.w = ca[k][t][s2][1].y;
;                         acc = __builtin_amdgcn_mfma_f32_16x16x32_bf16(__builtin_bit_cast(bf16x8, w), bfr[s2], acc, 0, 0, 0); }
;                     S[t][0] = acc[0]; S[t][1] = acc[1]; S[t][2] = acc[2]; S[t][3] = acc[3];
;                 }
;             }
;         }
.Lsg_loop:
	s_add_i32 s37, s39, 3
	s_min_u32 s37, s37, 0x7f
	s_lshl_b32 s38, s37, 13
	s_add_u32 s82, s44, s38
	s_addc_u32 s83, s45, 0
	global_load_dwordx2 v[48:49], v6, s[82:83]
	global_load_dwordx2 v[50:51], v6, s[82:83] offset:512
	global_load_dwordx2 v[52:53], v6, s[82:83] offset:1024
	global_load_dwordx2 v[54:55], v6, s[82:83] offset:1536
	s_add_u32 s82, s46, s38
	s_addc_u32 s83, s47, 0
	global_load_dwordx4 v[176:179], v7, s[82:83]
	global_load_dwordx4 v[184:187], v7, s[82:83] offset:1024
	global_load_dwordx4 v[188:191], v7, s[82:83] offset:2048
	global_load_dwordx4 v[192:195], v7, s[82:83] offset:3072
	global_load_dwordx4 v[196:199], v129, s[82:83]
	global_load_dwordx4 v[200:203], v129, s[82:83] offset:1024
	global_load_dwordx4 v[204:207], v129, s[82:83] offset:2048
	global_load_dwordx4 v[208:211], v129, s[82:83] offset:3072
	s_waitcnt vmcnt(56)
	v_cvt_pk_bf16_f32 v120, v8, v9
	v_cvt_pk_bf16_f32 v121, v10, v11
	v_cvt_pk_bf16_f32 v122, v12, v13
	v_cvt_pk_bf16_f32 v123, v14, v15
	v_cvt_pk_bf16_f32 v124, v16, v17
	v_cvt_pk_bf16_f32 v125, v18, v19
	v_cvt_pk_bf16_f32 v126, v20, v21
	v_cvt_pk_bf16_f32 v127, v22, v23
	s_add_i32 s37, s39, 0
	s_lshl_b32 s38, s37, 13
	s_add_u32 s40, s44, s38
	s_addc_u32 s41, s45, 0
	global_store_dwordx2 v6, v[120:121], s[40:41]
	global_store_dwordx2 v6, v[122:123], s[40:41] offset:512
	global_store_dwordx2 v6, v[124:125], s[40:41] offset:1024
	global_store_dwordx2 v6, v[126:127], s[40:41] offset:1536
	v_lshlrev_b32_e32 v8, 16, v24
	v_and_b32_e32 v9, 0xffff0000, v24
	v_lshlrev_b32_e32 v10, 16, v25
	v_and_b32_e32 v11, 0xffff0000, v25
	v_lshlrev_b32_e32 v12, 16, v26
	v_and_b32_e32 v13, 0xffff0000, v26
	v_lshlrev_b32_e32 v14, 16, v27
	v_and_b32_e32 v15, 0xffff0000, v27
	v_lshlrev_b32_e32 v16, 16, v28
	v_and_b32_e32 v17, 0xffff0000, v28
	v_lshlrev_b32_e32 v18, 16, v29
	v_and_b32_e32 v19, 0xffff0000, v29
	v_lshlrev_b32_e32 v20, 16, v30
	v_and_b32_e32 v21, 0xffff0000, v30
	v_lshlrev_b32_e32 v22, 16, v31
	v_and_b32_e32 v23, 0xffff0000, v31
	s_waitcnt vmcnt(52)
	v_mfma_f32_16x16x32_bf16 v[8:11], v[56:59], v[120:123], v[8:11]
	v_mfma_f32_16x16x32_bf16 v[12:15], v[64:67], v[120:123], v[12:15]
	v_mfma_f32_16x16x32_bf16 v[16:19], v[72:75], v[120:123], v[16:19]
	v_mfma_f32_16x16x32_bf16 v[20:23], v[80:83], v[120:123], v[20:23]
	v_mfma_f32_16x16x32_bf16 v[8:11], v[60:63], v[124:127], v[8:11]
	v_mfma_f32_16x16x32_bf16 v[12:15], v[68:71], v[124:127], v[12:15]
	v_mfma_f32_16x16x32_bf16 v[16:19], v[76:79], v[124:127], v[16:19]
	v_mfma_f32_16x16x32_bf16 v[20:23], v[84:87], v[124:127], v[20:23]
	s_add_i32 s37, s39, 4
	s_min_u32 s37, s37, 0x7f
	s_lshl_b32 s38, s37, 13
	s_add_u32 s82, s44, s38
	s_addc_u32 s83, s45, 0
	global_load_dwordx2 v[24:25], v6, s[82:83]
	global_load_dwordx2 v[26:27], v6, s[82:83] offset:512
	global_load_dwordx2 v[28:29], v6, s[82:83] offset:1024
	global_load_dwordx2 v[30:31], v6, s[82:83] offset:1536
	s_add_u32 s82, s46, s38
	s_addc_u32 s83, s47, 0
	global_load_dwordx4 v[56:59], v7, s[82:83]
	global_load_dwordx4 v[60:63], v7, s[82:83] offset:1024
	global_load_dwordx4 v[64:67], v7, s[82:83] offset:2048
	global_load_dwordx4 v[68:71], v7, s[82:83] offset:3072
	global_load_dwordx4 v[72:75], v129, s[82:83]
	global_load_dwordx4 v[76:79], v129, s[82:83] offset:1024
	global_load_dwordx4 v[80:83], v129, s[82:83] offset:2048
	global_load_dwordx4 v[84:87], v129, s[82:83] offset:3072
	s_waitcnt vmcnt(56)
	v_cvt_pk_bf16_f32 v120, v8, v9
	v_cvt_pk_bf16_f32 v121, v10, v11
	v_cvt_pk_bf16_f32 v122, v12, v13
	v_cvt_pk_bf16_f32 v123, v14, v15
	v_cvt_pk_bf16_f32 v124, v16, v17
	v_cvt_pk_bf16_f32 v125, v18, v19
	v_cvt_pk_bf16_f32 v126, v20, v21
	v_cvt_pk_bf16_f32 v127, v22, v23
	s_add_i32 s37, s39, 1
	s_lshl_b32 s38, s37, 13
	s_add_u32 s40, s44, s38
	s_addc_u32 s41, s45, 0
	global_store_dwordx2 v6, v[120:121], s[40:41]
	global_store_dwordx2 v6, v[122:123], s[40:41] offset:512
	global_store_dwordx2 v6, v[124:125], s[40:41] offset:1024
	global_store_dwordx2 v6, v[126:127], s[40:41] offset:1536
	v_lshlrev_b32_e32 v8, 16, v32
	v_and_b32_e32 v9, 0xffff0000, v32
	v_lshlrev_b32_e32 v10, 16, v33
	v_and_b32_e32 v11, 0xffff0000, v33
	v_lshlrev_b32_e32 v12, 16, v34
	v_and_b32_e32 v13, 0xffff0000, v34
	v_lshlrev_b32_e32 v14, 16, v35
	v_and_b32_e32 v15, 0xffff0000, v35
	v_lshlrev_b32_e32 v16, 16, v36
	v_and_b32_e32 v17, 0xffff0000, v36
	v_lshlrev_b32_e32 v18, 16, v37
	v_and_b32_e32 v19, 0xffff0000, v37
	v_lshlrev_b32_e32 v20, 16, v38
	v_and_b32_e32 v21, 0xffff0000, v38
	v_lshlrev_b32_e32 v22, 16, v39
	v_and_b32_e32 v23, 0xffff0000, v39
	s_waitcnt vmcnt(52)
; __device__ __forceinline__ float bf_lo(unsigned u) { return __uint_as_float(u << 16); }
; __device__ __forceinline__ float bf_hi(unsigned u) { return __uint_as_float(u & 0xffff0000u); }
; __device__ __forceinline__ unsigned pk2(float lo, float hi) { return pg8::cvt_pk_bf16(lo, hi); }
; __device__ __forceinline__ void scan_phase(const Ctx& X, int wave, int lane) {
;     ...
;         SCAN_LOAD_G(0, 0) SCAN_LOAD_G(1, 1) SCAN_LOAD_G(2, 2)
; #pragma unroll 1
;         for (int c0 = 0; c0 < NCH; c0 += 4) {
; #pragma unroll
;             for (int k = 0; k < 4; ++k) {
;                 const int c = c0 + k;
;                 SCAN_LOAD_G((k + 3) & 3, c + 3)
;                 bf16_t* bcc = bc0 + (size_t)c * 4096;
;                 u32x2 sp[4];
; #pragma unroll
;                 for (int t = 0; t < 4; ++t) { sp[t].x = pk2(S[t][0], S[t][1]); sp[t].y = pk2(S[t][2], S[t][3]);
;                     asm volatile("" : "+v"(sp[t].x) : "v"(cb[k][t].x));
;                     *(u32x2*)(bcc + 256 * t) = sp[t]; }
;                 bf16x8 bfr[2];
; #pragma unroll
;                 for (int s2 = 0; s2 < 2; ++s2) { u32x4 w; w.x = sp[2 * s2].x; w.y = sp[2 * s2].y; w.z = sp[2 * s2 + 1].x; w.w = sp[2 * s2 + 1].y; bfr[s2] = __builtin_bit_cast(bf16x8, w); }
; #pragma unroll
;                 for (int t = 0; t < 4; ++t) {
;                     f32x4 acc = (f32x4){bf_lo(cb[k][t].x), bf_hi(cb[k][t].x), bf_lo(cb[k][t].y), bf_hi(cb[k][t].y)};
; #pragma unroll
;                     for (int s2 = 0; s2 < 2; ++s2) { u32x4 w; w.x = ca[k][t][s2][0].x; w.y = ca[k][t][s2][0].y; w.z = ca[k][t][s2][1].x; w.w = ca[k][t][s2][1].y;
;                         acc = __builtin_amdgcn_mfma_f32_16x16x32_bf16(__builtin_bit_cast(bf16x8, w), bfr[s2], acc, 0, 0, 0); }
;                     S[t][0] = acc[0]; S[t][1] = acc[1]; S[t][2] = acc[2]; S[t][3] = acc[3];
;                 }
;             }
;         }
	v_mfma_f32_16x16x32_bf16 v[8:11], v[88:91], v[120:123], v[8:11]
	v_mfma_f32_16x16x32_bf16 v[12:15], v[96:99], v[120:123], v[12:15]
	v_mfma_f32_16x16x32_bf16 v[16:19], v[104:107], v[120:123], v[16:19]
	v_mfma_f32_16x16x32_bf16 v[20:23], v[112:115], v[120:123], v[20:23]
	v_mfma_f32_16x16x32_bf16 v[8:11], v[92:95], v[124:127], v[8:11]
	v_mfma_f32_16x16x32_bf16 v[12:15], v[100:103], v[124:127], v[12:15]
	v_mfma_f32_16x16x32_bf16 v[16:19], v[108:111], v[124:127], v[16:19]
	v_mfma_f32_16x16x32_bf16 v[20:23], v[116:119], v[124:127], v[20:23]
	s_add_i32 s37, s39, 5
	s_min_u32 s37, s37, 0x7f
	s_lshl_b32 s38, s37, 13
	s_add_u32 s82, s44, s38
	s_addc_u32 s83, s45, 0
	global_load_dwordx2 v[32:33], v6, s[82:83]
	global_load_dwordx2 v[34:35], v6, s[82:83] offset:512
	global_load_dwordx2 v[36:37], v6, s[82:83] offset:1024
	global_load_dwordx2 v[38:39], v6, s[82:83] offset:1536
	s_add_u32 s82, s46, s38
	s_addc_u32 s83, s47, 0
	global_load_dwordx4 v[88:91], v7, s[82:83]
	global_load_dwordx4 v[92:95], v7, s[82:83] offset:1024
	global_load_dwordx4 v[96:99], v7, s[82:83] offset:2048
	global_load_dwordx4 v[100:103], v7, s[82:83] offset:3072
	global_load_dwordx4 v[104:107], v129, s[82:83]
	global_load_dwordx4 v[108:111], v129, s[82:83] offset:1024
	global_load_dwordx4 v[112:115], v129, s[82:83] offset:2048
	global_load_dwordx4 v[116:119], v129, s[82:83] offset:3072
	s_waitcnt vmcnt(56)
	v_cvt_pk_bf16_f32 v120, v8, v9
	v_cvt_pk_bf16_f32 v121, v10, v11
	v_cvt_pk_bf16_f32 v122, v12, v13
	v_cvt_pk_bf16_f32 v123, v14, v15
	v_cvt_pk_bf16_f32 v124, v16, v17
	v_cvt_pk_bf16_f32 v125, v18, v19
	v_cvt_pk_bf16_f32 v126, v20, v21
	v_cvt_pk_bf16_f32 v127, v22, v23
	s_add_i32 s37, s39, 2
	s_lshl_b32 s38, s37, 13
	s_add_u32 s40, s44, s38
	s_addc_u32 s41, s45, 0
	global_store_dwordx2 v6, v[120:121], s[40:41]
	global_store_dwordx2 v6, v[122:123], s[40:41] offset:512
	global_store_dwordx2 v6, v[124:125], s[40:41] offset:1024
	global_store_dwordx2 v6, v[126:127], s[40:41] offset:1536
	v_lshlrev_b32_e32 v8, 16, v40
	v_and_b32_e32 v9, 0xffff0000, v40
	v_lshlrev_b32_e32 v10, 16, v41
	v_and_b32_e32 v11, 0xffff0000, v41
	v_lshlrev_b32_e32 v12, 16, v42
	v_and_b32_e32 v13, 0xffff0000, v42
	v_lshlrev_b32_e32 v14, 16, v43
	v_and_b32_e32 v15, 0xffff0000, v43
	v_lshlrev_b32_e32 v16, 16, v44
	v_and_b32_e32 v17, 0xffff0000, v44
	v_lshlrev_b32_e32 v18, 16, v45
	v_and_b32_e32 v19, 0xffff0000, v45
	v_lshlrev_b32_e32 v20, 16, v46
	v_and_b32_e32 v21, 0xffff0000, v46
	v_lshlrev_b32_e32 v22, 16, v47
	v_and_b32_e32 v23, 0xffff0000, v47
	s_waitcnt vmcnt(52)
	v_mfma_f32_16x16x32_bf16 v[8:11], v[132:135], v[120:123], v[8:11]
	v_mfma_f32_16x16x32_bf16 v[12:15], v[140:143], v[120:123], v[12:15]
	v_mfma_f32_16x16x32_bf16 v[16:19], v[148:151], v[120:123], v[16:19]
	v_mfma_f32_16x16x32_bf16 v[20:23], v[168:171], v[120:123], v[20:23]
	v_mfma_f32_16x16x32_bf16 v[8:11], v[136:139], v[124:127], v[8:11]
	v_mfma_f32_16x16x32_bf16 v[12:15], v[144:147], v[124:127], v[12:15]
	v_mfma_f32_16x16x32_bf16 v[16:19], v[164:167], v[124:127], v[16:19]
	v_mfma_f32_16x16x32_bf16 v[20:23], v[172:175], v[124:127], v[20:23]
	s_add_i32 s37, s39, 6
	s_min_u32 s37, s37, 0x7f
	s_lshl_b32 s38, s37, 13
	s_add_u32 s82, s44, s38
	s_addc_u32 s83, s45, 0
	global_load_dwordx2 v[40:41], v6, s[82:83]
	global_load_dwordx2 v[42:43], v6, s[82:83] offset:512
	global_load_dwordx2 v[44:45], v6, s[82:83] offset:1024
	global_load_dwordx2 v[46:47], v6, s[82:83] offset:1536
	s_add_u32 s82, s46, s38
	s_addc_u32 s83, s47, 0
	global_load_dwordx4 v[132:135], v7, s[82:83]
	global_load_dwordx4 v[136:139], v7, s[82:83] offset:1024
	global_load_dwordx4 v[140:143], v7, s[82:83] offset:2048
	global_load_dwordx4 v[144:147], v7, s[82:83] offset:3072
	global_load_dwordx4 v[148:151], v129, s[82:83]
	global_load_dwordx4 v[164:167], v129, s[82:83] offset:1024
	global_load_dwordx4 v[168:171], v129, s[82:83] offset:2048
	global_load_dwordx4 v[172:175], v129, s[82:83] offset:3072
	s_waitcnt vmcnt(56)
	v_cvt_pk_bf16_f32 v120, v8, v9
	v_cvt_pk_bf16_f32 v121, v10, v11
	v_cvt_pk_bf16_f32 v122, v12, v13
	v_cvt_pk_bf16_f32 v123, v14, v15
	v_cvt_pk_bf16_f32 v124, v16, v17
	v_cvt_pk_bf16_f32 v125, v18, v19
	v_cvt_pk_bf16_f32 v126, v20, v21
	v_cvt_pk_bf16_f32 v127, v22, v23
	s_add_i32 s37, s39, 3
	s_lshl_b32 s38, s37, 13
	s_add_u32 s40, s44, s38
	s_addc_u32 s41, s45, 0
	global_store_dwordx2 v6, v[120:121], s[40:41]
	global_store_dwordx2 v6, v[122:123], s[40:41] offset:512
	global_store_dwordx2 v6, v[124:125], s[40:41] offset:1024
	global_store_dwordx2 v6, v[126:127], s[40:41] offset:1536
	v_lshlrev_b32_e32 v8, 16, v48
	v_and_b32_e32 v9, 0xffff0000, v48
	v_lshlrev_b32_e32 v10, 16, v49
	v_and_b32_e32 v11, 0xffff0000, v49
	v_lshlrev_b32_e32 v12, 16, v50
	v_and_b32_e32 v13, 0xffff0000, v50
	v_lshlrev_b32_e32 v14, 16, v51
	v_and_b32_e32 v15, 0xffff0000, v51
	v_lshlrev_b32_e32 v16, 16, v52
	v_and_b32_e32 v17, 0xffff0000, v52
	v_lshlrev_b32_e32 v18, 16, v53
	v_and_b32_e32 v19, 0xffff0000, v53
	v_lshlrev_b32_e32 v20, 16, v54
	v_and_b32_e32 v21, 0xffff0000, v54
	v_lshlrev_b32_e32 v22, 16, v55
	v_and_b32_e32 v23, 0xffff0000, v55
	s_waitcnt vmcnt(52)
	v_mfma_f32_16x16x32_bf16 v[8:11], v[176:179], v[120:123], v[8:11]
	v_mfma_f32_16x16x32_bf16 v[12:15], v[188:191], v[120:123], v[12:15]
	v_mfma_f32_16x16x32_bf16 v[16:19], v[196:199], v[120:123], v[16:19]
	v_mfma_f32_16x16x32_bf16 v[20:23], v[204:207], v[120:123], v[20:23]
	v_mfma_f32_16x16x32_bf16 v[8:11], v[184:187], v[124:127], v[8:11]
	v_mfma_f32_16x16x32_bf16 v[12:15], v[192:195], v[124:127], v[12:15]
	v_mfma_f32_16x16x32_bf16 v[16:19], v[200:203], v[124:127], v[16:19]
	v_mfma_f32_16x16x32_bf16 v[20:23], v[208:211], v[124:127], v[20:23]
	s_add_i32 s39, s39, 4
	s_cmpk_lt_u32 s39, 0x80
	s_cbranch_scc1 .Lsg_loop
	s_branch .LBB0_739
